# grid barrier poll loops: s_sleep 1 replaced by s_nop 0 (poll as fast as the round trip allows)
# speedup vs baseline: 1.0034x; 1.0034x over previous
; __device__ __forceinline__ unsigned xb_ld(unsigned* p)              { return __hip_atomic_load(p, __ATOMIC_RELAXED, __HIP_MEMORY_SCOPE_AGENT); }
; __device__ __forceinline__ void xcd_barrier_complete(unsigned* bar, unsigned x, unsigned& nloc, unsigned& nx) {
;     const unsigned G = gridDim.x * gridDim.y * gridDim.z;
;     unsigned sum, cnt, mine, sp = 0u;
;     for (;;) {
;         sum = 0u; cnt = 0u; mine = 0u;
; #pragma unroll
;         for (unsigned j = 0; j < 16; ++j) { const unsigned c = xb_ld(&bar[XB_XCNT(j)]); sum += c; cnt += (c > 0u) ? 1u : 0u; mine = (j == x) ? c : mine; }
;         if (sum == G) break;
;         __builtin_amdgcn_s_sleep(1);
;         if ((++sp & 255u) == 0u) { if (xb_ld(&bar[XB_TMO])) break; if (sp > XB_SPIN_CAP) { atomicAdd(&bar[XB_TMO], 1u); break; } }
;     }
;     nloc = mine > 0u ? mine : 1u; nx = cnt > 0u ? cnt : 1u;
; }
.LBB0_1272:
	v_mov_b64_e32 v[12:13], s[34:35]
	flat_load_dword v2, v[12:13] offset:1024 sc1
	s_waitcnt lgkmcnt(0)
	flat_load_dword v0, v[12:13] offset:1280 sc1
	flat_load_dword v3, v[12:13] offset:1536 sc1
	v_readlane_b32 s16, v254, 38
	s_or_b64 s[14:15], s[14:15], exec
	s_or_b64 s[12:13], s[12:13], exec
	s_waitcnt vmcnt(0) lgkmcnt(0)
	v_add_u32_e32 v4, v0, v2
	v_add_u32_e32 v5, v4, v3
	flat_load_dword v4, v[12:13] offset:1792 sc1
	s_waitcnt vmcnt(0) lgkmcnt(0)
	v_add_u32_e32 v6, v5, v4
	flat_load_dword v5, v[12:13] offset:2048 sc1
	s_waitcnt vmcnt(0) lgkmcnt(0)
	v_add_u32_e32 v7, v6, v5
	flat_load_dword v6, v[12:13] offset:2304 sc1
	s_waitcnt vmcnt(0) lgkmcnt(0)
	v_add_u32_e32 v8, v7, v6
	flat_load_dword v7, v[12:13] offset:2560 sc1
	s_waitcnt vmcnt(0) lgkmcnt(0)
	v_add_u32_e32 v9, v8, v7
	flat_load_dword v8, v[12:13] offset:2816 sc1
	s_waitcnt vmcnt(0) lgkmcnt(0)
	v_add_u32_e32 v10, v9, v8
	flat_load_dword v9, v[12:13] offset:3072 sc1
	s_waitcnt vmcnt(0) lgkmcnt(0)
	v_add_u32_e32 v11, v10, v9
	flat_load_dword v10, v[12:13] offset:3328 sc1
	s_waitcnt vmcnt(0) lgkmcnt(0)
	v_add_u32_e32 v14, v11, v10
	flat_load_dword v11, v[12:13] offset:3584 sc1
	s_waitcnt vmcnt(0) lgkmcnt(0)
	v_add_u32_e32 v14, v14, v11
	flat_load_dword v12, v[12:13] offset:3840 sc1
	s_waitcnt vmcnt(0) lgkmcnt(0)
	v_add_u32_e32 v16, v14, v12
	v_mov_b64_e32 v[14:15], s[0:1]
	flat_load_dword v13, v[14:15] sc1
	v_mov_b64_e32 v[14:15], s[2:3]
	flat_load_dword v14, v[14:15] sc1
	s_waitcnt vmcnt(0) lgkmcnt(0)
	v_add_u32_e32 v16, v16, v13
	v_add_u32_e32 v18, v16, v14
	v_mov_b64_e32 v[16:17], s[4:5]
	flat_load_dword v15, v[16:17] sc1
	v_mov_b64_e32 v[16:17], s[6:7]
	flat_load_dword v16, v[16:17] sc1
	s_waitcnt vmcnt(0) lgkmcnt(0)
	v_add_u32_e32 v18, v18, v15
	v_add_u32_e32 v17, v18, v16
	v_cmp_ne_u32_e32 vcc, s16, v17
	s_and_saveexec_b64 s[16:17], vcc
	s_cbranch_execz .LBB0_1271
	s_and_b32 s20, s26, 0xff
	s_mov_b64 s[18:19], -1
	s_cmp_eq_u32 s20, 0
	s_mov_b64 s[22:23], -1
	s_mov_b64 s[20:21], -1
	s_nop 0
	s_cbranch_scc1 .LBB0_1275
	s_and_saveexec_b64 s[24:25], s[22:23]
	s_cbranch_execz .LBB0_1270
	s_branch .LBB0_1278

; __device__ __forceinline__ unsigned xb_ld(unsigned* p)              { return __hip_atomic_load(p, __ATOMIC_RELAXED, __HIP_MEMORY_SCOPE_AGENT); }
; __device__ __forceinline__ unsigned xb_add(unsigned* p, unsigned v) { return __hip_atomic_fetch_add(p, v, __ATOMIC_RELAXED, __HIP_MEMORY_SCOPE_AGENT); }
; #define XB_SPIN(cond, bar) do { unsigned _sp = 0; while (cond) { __builtin_amdgcn_s_sleep(1); \
;     if ((++_sp & 255u) == 0u) { if (xb_ld(&(bar)[XB_TMO])) break; if (_sp > XB_SPIN_CAP) { atomicAdd(&(bar)[XB_TMO], 1u); break; } } } } while (0)
; __device__ __forceinline__ void xcd_barrier(const XcdBarrier& b) {
;     ...
;         if (old + 1u == (gen + 1u) * nloc) {
;             __builtin_amdgcn_fence(__ATOMIC_RELEASE, "agent");
;             asm volatile("s_waitcnt vmcnt(0)" ::: "memory");
;             const unsigned og = xb_add(&bar[XB_TOP], 1u);
;             const unsigned tg = og / nx;
;             if (og + 1u == (tg + 1u) * nx) xb_add(&bar[XB_TOPGEN], 1u);
;             else XB_SPIN(xb_ld(&bar[XB_TOPGEN]) == tg, bar);
;             __builtin_amdgcn_fence(__ATOMIC_ACQUIRE, "agent");
;             xb_add(&bar[XB_XGEN(bx_)], 1u);
;             asm volatile("s_waitcnt vmcnt(0)" ::: "memory");
;         } else {
;             XB_SPIN(xb_ld(&bar[XB_XGEN(bx_)]) == gen, bar);
.LBB0_1286:
	s_and_b32 s14, s21, 0xff
	s_mov_b64 s[12:13], -1
	s_cmp_lg_u32 s14, 0
	s_mov_b64 s[14:15], -1
	s_nop 0
	s_cbranch_scc1 .LBB0_1290
	v_mov_b64_e32 v[4:5], s[34:35]
	flat_load_dword v0, v[4:5] offset:512 sc1
	s_mov_b64 s[14:15], 0
	s_mov_b64 s[16:17], -1
	s_waitcnt vmcnt(0) lgkmcnt(0)
	v_cmp_eq_u32_e32 vcc, 0, v0
	s_and_saveexec_b64 s[18:19], vcc
	s_cmp_lt_u32 s21, 0x400001
	s_cselect_b64 s[14:15], -1, 0
	s_xor_b64 s[16:17], exec, -1
	s_and_b64 s[14:15], s[14:15], exec
	s_or_b64 exec, exec, s[18:19]

; __device__ __forceinline__ unsigned xb_ld(unsigned* p)              { return __hip_atomic_load(p, __ATOMIC_RELAXED, __HIP_MEMORY_SCOPE_AGENT); }
; __device__ __forceinline__ unsigned xb_add(unsigned* p, unsigned v) { return __hip_atomic_fetch_add(p, v, __ATOMIC_RELAXED, __HIP_MEMORY_SCOPE_AGENT); }
; #define XB_SPIN(cond, bar) do { unsigned _sp = 0; while (cond) { __builtin_amdgcn_s_sleep(1); \
;     if ((++_sp & 255u) == 0u) { if (xb_ld(&(bar)[XB_TMO])) break; if (_sp > XB_SPIN_CAP) { atomicAdd(&(bar)[XB_TMO], 1u); break; } } } } while (0)
; __device__ __forceinline__ void xcd_barrier(const XcdBarrier& b) {
;     ...
;         if (old + 1u == (gen + 1u) * nloc) {
;             __builtin_amdgcn_fence(__ATOMIC_RELEASE, "agent");
;             asm volatile("s_waitcnt vmcnt(0)" ::: "memory");
;             const unsigned og = xb_add(&bar[XB_TOP], 1u);
;             const unsigned tg = og / nx;
;             if (og + 1u == (tg + 1u) * nx) xb_add(&bar[XB_TOPGEN], 1u);
;             else XB_SPIN(xb_ld(&bar[XB_TOPGEN]) == tg, bar);
;             __builtin_amdgcn_fence(__ATOMIC_ACQUIRE, "agent");
;             xb_add(&bar[XB_XGEN(bx_)], 1u);
;             asm volatile("s_waitcnt vmcnt(0)" ::: "memory");
;         } else {
;             XB_SPIN(xb_ld(&bar[XB_XGEN(bx_)]) == gen, bar);
.LBB0_1300:
	s_and_b32 s14, s21, 0xff
	s_mov_b64 s[12:13], -1
	s_cmp_lg_u32 s14, 0
	s_mov_b64 s[16:17], -1
	s_nop 0
	s_cbranch_scc0 .LBB0_1302
	s_and_saveexec_b64 s[18:19], s[16:17]
	s_cbranch_execz .LBB0_1299
	s_branch .LBB0_1305
